# speedup vs baseline: 1.0380x; 1.0005x over previous
;   DEVINL void operator()(Acc& acc, int brow, int bcol) const {
;     ...
;     } else if (tt < 8) {
;       const int head = tt - 4;
;       _Pragma("unroll") for (int ai = 0; ai < 2; ++ai) _Pragma("unroll") for (int bj = 0; bj < 2; ++bj) _Pragma("unroll") for (int m = 0; m < 4; ++m) _Pragma("unroll") for (int n = 0; n < 2; ++n) {
;         const int row0 = brow + ai * 128 + wr * 64 + m * 16 + fq * 4;
;         const int e = wc * 64 + fr * 4 + bj * 2 + n;
;         const int chunk = row0 >> 7, m0 = row0 & 127;
;         const f32x4 v = acc[ai][bj][m][n];
;         *(bf16x4*)(P.vT + ((size_t)(chunk * 4 + head) * 256 + e) * 128 + m0) = pack4(v[0], v[1], v[2], v[3]);
;       }
.LBB0_760:
	s_andn2_b64 vcc, exec, s[8:9]
	s_cbranch_vccnz .LBB0_762
	s_load_dwordx2 s[8:9], s[88:89], 0x1a8
	v_and_b32_e32 v184, 63, v147
	v_lshrrev_b32_e32 v185, 6, v147
	v_and_b32_e32 v186, 3, v185
	v_mul_u32_u24_e32 v186, 0x1200, v186
	v_lshrrev_b32_e32 v187, 2, v185
	v_lshl_add_u32 v186, v187, 16, v186
	v_add_u32_e32 v186, 0x8000, v186
	v_mul_u32_u24_e32 v188, 0x120, v146
	v_lshl_add_u32 v188, v145, 3, v188
	v_add_u32_e32 v188, v188, v186
	v_lshrrev_b32_e32 v189, 3, v184
	v_mul_u32_u24_e32 v189, 0x90, v189
	v_and_b32_e32 v190, 7, v184
	v_lshl_add_u32 v189, v190, 4, v189
	v_add_u32_e32 v189, v189, v186
	s_lshr_b32 s10, s12, 7
	s_lshl_b32 s10, s10, 2
	s_add_i32 s10, s10, s37
	s_add_i32 s10, s10, -4
	s_lshl_b32 s10, s10, 16
	v_lshlrev_b32_e32 v191, 14, v149
	v_lshl_add_u32 v191, v144, 7, v191
	v_lshl_add_u32 v191, v190, 4, v191
	v_lshrrev_b32_e32 v192, 4, v184
	v_lshl_add_u32 v191, v192, 10, v191
	v_bfe_u32 v192, v184, 3, 1
	v_lshl_add_u32 v191, v192, 8, v191
	v_add_u32_e32 v191, s10, v191
	v_cvt_pk_bf16_f32 v194, v118, v119
	v_cvt_pk_bf16_f32 v195, v120, v121
	ds_write_b64 v188, v[194:195]
	v_cvt_pk_bf16_f32 v196, v114, v115
	v_cvt_pk_bf16_f32 v197, v116, v117
	ds_write_b64 v188, v[196:197] offset:144
	v_cvt_pk_bf16_f32 v198, v102, v103
	v_cvt_pk_bf16_f32 v199, v104, v105
	ds_write_b64 v188, v[198:199] offset:32
	v_cvt_pk_bf16_f32 v200, v98, v99
	v_cvt_pk_bf16_f32 v201, v100, v101
	ds_write_b64 v188, v[200:201] offset:176
	v_cvt_pk_bf16_f32 v202, v86, v87
	v_cvt_pk_bf16_f32 v203, v88, v89
	ds_write_b64 v188, v[202:203] offset:64
	v_cvt_pk_bf16_f32 v204, v82, v83
	v_cvt_pk_bf16_f32 v205, v84, v85
	ds_write_b64 v188, v[204:205] offset:208
	v_cvt_pk_bf16_f32 v206, v70, v71
	v_cvt_pk_bf16_f32 v207, v72, v73
	ds_write_b64 v188, v[206:207] offset:96
	v_cvt_pk_bf16_f32 v208, v66, v67
	v_cvt_pk_bf16_f32 v209, v68, v69
	ds_write_b64 v188, v[208:209] offset:240
	ds_read_b128 v[210:213], v189
	ds_read_b128 v[214:217], v189 offset:1152
	ds_read_b128 v[218:221], v189 offset:2304
	ds_read_b128 v[222:225], v189 offset:3456
	s_waitcnt lgkmcnt(0)
	v_add_u32_e32 v193, 0x0, v191
	global_store_dwordx4 v193, v[210:213], s[8:9]
	v_add_u32_e32 v193, 0x1000, v191
	global_store_dwordx4 v193, v[214:217], s[8:9]
	v_add_u32_e32 v193, 0x2000, v191
	global_store_dwordx4 v193, v[218:221], s[8:9]
	v_add_u32_e32 v193, 0x3000, v191
	global_store_dwordx4 v193, v[222:225], s[8:9]
	v_cvt_pk_bf16_f32 v194, v126, v127
	v_cvt_pk_bf16_f32 v195, v128, v129
	ds_write_b64 v188, v[194:195]
	v_cvt_pk_bf16_f32 v196, v122, v123
	v_cvt_pk_bf16_f32 v197, v124, v125
	ds_write_b64 v188, v[196:197] offset:144
	v_cvt_pk_bf16_f32 v198, v110, v111
	v_cvt_pk_bf16_f32 v199, v112, v113
	ds_write_b64 v188, v[198:199] offset:32
	v_cvt_pk_bf16_f32 v200, v106, v107
	v_cvt_pk_bf16_f32 v201, v108, v109
	ds_write_b64 v188, v[200:201] offset:176
	v_cvt_pk_bf16_f32 v202, v94, v95
	v_cvt_pk_bf16_f32 v203, v96, v97
	ds_write_b64 v188, v[202:203] offset:64
	v_cvt_pk_bf16_f32 v204, v90, v91
	v_cvt_pk_bf16_f32 v205, v92, v93
	ds_write_b64 v188, v[204:205] offset:208
	v_cvt_pk_bf16_f32 v206, v78, v79
	v_cvt_pk_bf16_f32 v207, v80, v81
	ds_write_b64 v188, v[206:207] offset:96
	v_cvt_pk_bf16_f32 v208, v74, v75
	v_cvt_pk_bf16_f32 v209, v76, v77
	ds_write_b64 v188, v[208:209] offset:240
	ds_read_b128 v[152:155], v189
	ds_read_b128 v[156:159], v189 offset:1152
	ds_read_b128 v[160:163], v189 offset:2304
	ds_read_b128 v[164:167], v189 offset:3456
	s_waitcnt lgkmcnt(3)
	v_add_u32_e32 v193, 0x0, v191
	global_store_dwordx4 v193, v[152:155], s[8:9] offset:512
	s_waitcnt lgkmcnt(2)
	v_add_u32_e32 v193, 0x1000, v191
	global_store_dwordx4 v193, v[156:159], s[8:9] offset:512
	s_waitcnt lgkmcnt(1)
	v_add_u32_e32 v193, 0x2000, v191
	global_store_dwordx4 v193, v[160:163], s[8:9] offset:512
	s_waitcnt lgkmcnt(0)
	v_add_u32_e32 v193, 0x3000, v191
	global_store_dwordx4 v193, v[164:167], s[8:9] offset:512
	v_cvt_pk_bf16_f32 v194, v54, v55
	v_cvt_pk_bf16_f32 v195, v56, v57
	ds_write_b64 v188, v[194:195]
	v_cvt_pk_bf16_f32 v196, v50, v51
	v_cvt_pk_bf16_f32 v197, v52, v53
	ds_write_b64 v188, v[196:197] offset:144
	v_cvt_pk_bf16_f32 v198, v38, v39
	v_cvt_pk_bf16_f32 v199, v40, v41
	ds_write_b64 v188, v[198:199] offset:32
	v_cvt_pk_bf16_f32 v200, v34, v35
	v_cvt_pk_bf16_f32 v201, v36, v37
	ds_write_b64 v188, v[200:201] offset:176
	v_cvt_pk_bf16_f32 v202, v22, v23
	v_cvt_pk_bf16_f32 v203, v24, v25
	ds_write_b64 v188, v[202:203] offset:64
	v_cvt_pk_bf16_f32 v204, v18, v19
	v_cvt_pk_bf16_f32 v205, v20, v21
	ds_write_b64 v188, v[204:205] offset:208
	v_cvt_pk_bf16_f32 v206, v6, v7
	v_cvt_pk_bf16_f32 v207, v8, v9
	ds_write_b64 v188, v[206:207] offset:96
	v_cvt_pk_bf16_f32 v208, v2, v3
	v_cvt_pk_bf16_f32 v209, v4, v5
	ds_write_b64 v188, v[208:209] offset:240
	ds_read_b128 v[210:213], v189
	ds_read_b128 v[214:217], v189 offset:1152
	ds_read_b128 v[218:221], v189 offset:2304
	ds_read_b128 v[222:225], v189 offset:3456
	s_waitcnt lgkmcnt(3)
	v_add_u32_e32 v193, 0x40000, v191
	global_store_dwordx4 v193, v[210:213], s[8:9]
	s_waitcnt lgkmcnt(2)
	v_add_u32_e32 v193, 0x41000, v191
	global_store_dwordx4 v193, v[214:217], s[8:9]
	s_waitcnt lgkmcnt(1)
	v_add_u32_e32 v193, 0x42000, v191
	global_store_dwordx4 v193, v[218:221], s[8:9]
	s_waitcnt lgkmcnt(0)
	v_add_u32_e32 v193, 0x43000, v191
	global_store_dwordx4 v193, v[222:225], s[8:9]
	v_cvt_pk_bf16_f32 v194, v62, v63
	v_cvt_pk_bf16_f32 v195, v64, v65
	ds_write_b64 v188, v[194:195]
	v_cvt_pk_bf16_f32 v196, v58, v59
	v_cvt_pk_bf16_f32 v197, v60, v61
	ds_write_b64 v188, v[196:197] offset:144
	v_cvt_pk_bf16_f32 v198, v46, v47
	v_cvt_pk_bf16_f32 v199, v48, v49
	ds_write_b64 v188, v[198:199] offset:32
	v_cvt_pk_bf16_f32 v200, v42, v43
	v_cvt_pk_bf16_f32 v201, v44, v45
	ds_write_b64 v188, v[200:201] offset:176
	v_cvt_pk_bf16_f32 v202, v30, v31
	v_cvt_pk_bf16_f32 v203, v32, v33
	ds_write_b64 v188, v[202:203] offset:64
	v_cvt_pk_bf16_f32 v204, v26, v27
	v_cvt_pk_bf16_f32 v205, v28, v29
	ds_write_b64 v188, v[204:205] offset:208
	v_cvt_pk_bf16_f32 v206, v14, v15
	v_cvt_pk_bf16_f32 v207, v16, v17
	ds_write_b64 v188, v[206:207] offset:96
	v_cvt_pk_bf16_f32 v208, v10, v11
	v_cvt_pk_bf16_f32 v209, v12, v13
	ds_write_b64 v188, v[208:209] offset:240
	ds_read_b128 v[152:155], v189
	ds_read_b128 v[156:159], v189 offset:1152
	ds_read_b128 v[160:163], v189 offset:2304
	ds_read_b128 v[164:167], v189 offset:3456
	s_waitcnt lgkmcnt(3)
	v_add_u32_e32 v193, 0x40000, v191
	global_store_dwordx4 v193, v[152:155], s[8:9] offset:512
	s_waitcnt lgkmcnt(2)
	v_add_u32_e32 v193, 0x41000, v191
	global_store_dwordx4 v193, v[156:159], s[8:9] offset:512
	s_waitcnt lgkmcnt(1)
	v_add_u32_e32 v193, 0x42000, v191
	global_store_dwordx4 v193, v[160:163], s[8:9] offset:512
	s_waitcnt lgkmcnt(0)
	v_add_u32_e32 v193, 0x43000, v191
	global_store_dwordx4 v193, v[164:167], s[8:9] offset:512
	s_waitcnt lgkmcnt(0)
